# SSD conv: 12 row loads hoisted to loop top; SSD scan: global prefetch deepened to 2 chunk-steps with ping-pong register sets
# speedup vs baseline: 1.0349x; 1.0088x over previous
.LBB0_104:
	ds_read2_b64 v[62:65], v113 offset1:4
	ds_read2_b64 v[66:69], v115 offset1:4
	ds_read2_b64 v[96:99], v117 offset1:4
	ds_read2_b64 v[128:131], v119 offset1:4
	ds_read2_b64 v[132:135], v113 offset0:8 offset1:12
	v_cvt_pk_bf16_f32 v58, v30, v31
	v_cvt_pk_bf16_f32 v59, v32, v33
	v_cvt_pk_bf16_f32 v60, v26, v27
	v_cvt_pk_bf16_f32 v61, v28, v29
	v_add_u32_e32 v127, 0xd400, v120
	s_waitcnt lgkmcnt(4)
	v_mfma_f32_16x16x32_bf16 v[62:65], v[58:61], v[62:65], 0
	v_readlane_b32 s34, v255, 22
	s_lshl_b32 s88, s22, 7
	s_mov_b32 s23, s89
	s_waitcnt lgkmcnt(3)
	v_mfma_f32_16x16x32_bf16 v[66:69], v[58:61], v[66:69], 0
	v_lshl_add_u64 v[94:95], v[82:83], 0, s[88:89]
	s_and_b64 vcc, exec, s[18:19]
	s_waitcnt lgkmcnt(2)
	v_mfma_f32_16x16x32_bf16 v[96:99], v[58:61], v[96:99], 0
	s_waitcnt lgkmcnt(1)
	v_mfma_f32_16x16x32_bf16 v[58:61], v[58:61], v[128:131], 0
	v_cvt_pk_bf16_f32 v128, v38, v39
	v_cvt_pk_bf16_f32 v129, v40, v41
	v_cvt_pk_bf16_f32 v130, v34, v35
	v_cvt_pk_bf16_f32 v131, v36, v37
	s_waitcnt lgkmcnt(0)
	v_mfma_f32_16x16x32_bf16 v[62:65], v[128:131], v[132:135], v[62:65]
	ds_read2_b64 v[132:135], v115 offset0:8 offset1:12
	s_waitcnt lgkmcnt(0)
	v_mfma_f32_16x16x32_bf16 v[66:69], v[128:131], v[132:135], v[66:69]
	ds_read2_b64 v[132:135], v117 offset0:8 offset1:12
	s_waitcnt lgkmcnt(0)
	v_mfma_f32_16x16x32_bf16 v[96:99], v[128:131], v[132:135], v[96:99]
	ds_read2_b64 v[132:135], v119 offset0:8 offset1:12
	s_waitcnt lgkmcnt(0)
	v_mfma_f32_16x16x32_bf16 v[58:61], v[128:131], v[132:135], v[58:61]
	ds_read2_b64 v[132:135], v113 offset0:16 offset1:20
	v_cvt_pk_bf16_f32 v128, v46, v47
	v_cvt_pk_bf16_f32 v129, v48, v49
	v_cvt_pk_bf16_f32 v130, v42, v43
	v_cvt_pk_bf16_f32 v131, v44, v45
	s_waitcnt lgkmcnt(0)
	v_mfma_f32_16x16x32_bf16 v[62:65], v[128:131], v[132:135], v[62:65]
	ds_read2_b64 v[132:135], v115 offset0:16 offset1:20
	s_waitcnt lgkmcnt(0)
	v_mfma_f32_16x16x32_bf16 v[66:69], v[128:131], v[132:135], v[66:69]
	ds_read2_b64 v[132:135], v117 offset0:16 offset1:20
	s_waitcnt lgkmcnt(0)
	v_mfma_f32_16x16x32_bf16 v[96:99], v[128:131], v[132:135], v[96:99]
	ds_read2_b64 v[132:135], v119 offset0:16 offset1:20
	s_waitcnt lgkmcnt(0)
	v_mfma_f32_16x16x32_bf16 v[58:61], v[128:131], v[132:135], v[58:61]
	ds_read2_b64 v[132:135], v113 offset0:24 offset1:28
	v_cvt_pk_bf16_f32 v128, v54, v55
	v_cvt_pk_bf16_f32 v129, v56, v57
	v_cvt_pk_bf16_f32 v130, v50, v51
	v_cvt_pk_bf16_f32 v131, v52, v53
	s_waitcnt lgkmcnt(0)
	v_mfma_f32_16x16x32_bf16 v[62:65], v[128:131], v[132:135], v[62:65]
	ds_read2_b64 v[132:135], v115 offset0:24 offset1:28
	s_waitcnt lgkmcnt(0)
	v_mfma_f32_16x16x32_bf16 v[66:69], v[128:131], v[132:135], v[66:69]
	ds_read2_b64 v[132:135], v117 offset0:24 offset1:28
	s_waitcnt lgkmcnt(0)
	v_mfma_f32_16x16x32_bf16 v[132:135], v[128:131], v[132:135], v[96:99]
	s_nop 2
	ds_read2_b64 v[96:99], v119 offset0:24 offset1:28
	s_waitcnt lgkmcnt(0)
	v_mfma_f32_16x16x32_bf16 v[58:61], v[128:131], v[96:99], v[58:61]
	ds_read2_b32 v[96:97], v127 offset1:16
	s_waitcnt lgkmcnt(0)
	v_mul_f32_e32 v96, 0x3fb8aa3b, v96
	v_exp_f32_e32 v96, v96
	s_nop 0
	v_pk_mul_f32 v[62:63], v[62:63], v[96:97] op_sel_hi:[1,0]
	s_nop 0
	v_cvt_pk_bf16_f32 v100, v62, v63
	v_mul_f32_e32 v62, 0x3fb8aa3b, v97
	v_exp_f32_e32 v62, v62
	v_pk_mul_f32 v[64:65], v[64:65], v[96:97] op_sel_hi:[1,0]
	s_nop 0
	v_cvt_pk_bf16_f32 v101, v64, v65
	v_pk_mul_f32 v[64:65], v[68:69], v[62:63] op_sel_hi:[1,0]
	v_pk_mul_f32 v[62:63], v[66:67], v[62:63] op_sel_hi:[1,0]
	v_cvt_pk_bf16_f32 v99, v64, v65
	s_nop 0
	v_cvt_pk_bf16_f32 v98, v62, v63
	ds_read2_b32 v[62:63], v127 offset0:32 offset1:48
	s_waitcnt lgkmcnt(0)
	v_mul_f32_e32 v62, 0x3fb8aa3b, v62
	v_exp_f32_e32 v62, v62
	s_nop 0
	v_pk_mul_f32 v[64:65], v[134:135], v[62:63] op_sel_hi:[1,0]
	v_pk_mul_f32 v[66:67], v[132:133], v[62:63] op_sel_hi:[1,0]
	v_mul_f32_e32 v62, 0x3fb8aa3b, v63
	v_exp_f32_e32 v62, v62
	v_cvt_pk_bf16_f32 v66, v66, v67
	v_cvt_pk_bf16_f32 v67, v64, v65
	s_nop 0
	v_pk_mul_f32 v[58:59], v[58:59], v[62:63] op_sel_hi:[1,0]
	v_pk_mul_f32 v[60:61], v[60:61], v[62:63] op_sel_hi:[1,0]
	v_cvt_pk_bf16_f32 v96, v58, v59
	v_mov_b32_e32 v58, s34
	ds_read_b32 v58, v58 offset:54524
	v_cvt_pk_bf16_f32 v97, v60, v61
	s_waitcnt lgkmcnt(0)
	v_mul_f32_e32 v58, 0x3fb8aa3b, v58
	v_exp_f32_e32 v68, v58
	s_nop 0
	v_pk_mul_f32 v[60:61], v[68:69], v[28:29] op_sel_hi:[0,1]
	v_pk_mul_f32 v[58:59], v[68:69], v[26:27] op_sel_hi:[0,1]
	v_pk_mul_f32 v[64:65], v[68:69], v[36:37] op_sel_hi:[0,1]
	v_pk_mul_f32 v[62:63], v[68:69], v[34:35] op_sel_hi:[0,1]
	v_pk_mul_f32 v[130:131], v[68:69], v[44:45] op_sel_hi:[0,1]
	v_pk_mul_f32 v[128:129], v[68:69], v[42:43] op_sel_hi:[0,1]
	ds_read_b128 v[26:29], v121 offset:54784
	ds_read_b128 v[34:37], v121 offset:54800
	ds_read_b128 v[42:45], v122 offset:35840
	v_pk_mul_f32 v[132:133], v[68:69], v[54:55] op_sel_hi:[0,1]
	v_pk_mul_f32 v[134:135], v[68:69], v[56:57] op_sel_hi:[0,1]
	v_pk_mul_f32 v[32:33], v[68:69], v[32:33] op_sel_hi:[0,1]
	v_pk_mul_f32 v[30:31], v[68:69], v[30:31] op_sel_hi:[0,1]
	s_waitcnt lgkmcnt(0)
	v_lshlrev_b32_e32 v54, 16, v42
	v_and_b32_e32 v42, 0xffff0000, v42
	v_mul_f32_e32 v26, v26, v54
	v_mul_f32_e32 v27, v27, v42
	v_cvt_pk_bf16_f32 v54, v26, v27
	v_lshlrev_b32_e32 v26, 16, v43
	v_and_b32_e32 v27, 0xffff0000, v43
	v_mul_f32_e32 v26, v28, v26
	v_mul_f32_e32 v27, v29, v27
	v_cvt_pk_bf16_f32 v55, v26, v27
	v_lshlrev_b32_e32 v26, 16, v44
	v_and_b32_e32 v27, 0xffff0000, v44
	v_mul_f32_e32 v26, v34, v26
	v_mul_f32_e32 v27, v35, v27
	v_cvt_pk_bf16_f32 v56, v26, v27
	v_lshlrev_b32_e32 v26, 16, v45
	v_and_b32_e32 v27, 0xffff0000, v45
	v_mul_f32_e32 v26, v36, v26
	v_mul_f32_e32 v27, v37, v27
	v_cvt_pk_bf16_f32 v57, v26, v27
	ds_read_b128 v[26:29], v125 offset:17408
	ds_read_b128 v[34:37], v125 offset:22016
	s_waitcnt lgkmcnt(1)
	v_mfma_f32_16x16x32_bf16 v[26:29], v[26:29], v[54:57], v[30:33]
	s_nop 2
	ds_read_b128 v[30:33], v125 offset:19712
	v_pk_mul_f32 v[40:41], v[68:69], v[40:41] op_sel_hi:[0,1]
	v_pk_mul_f32 v[38:39], v[68:69], v[38:39] op_sel_hi:[0,1]
	ds_read_b128 v[42:45], v125 offset:26624
	v_pk_mul_f32 v[48:49], v[68:69], v[48:49] op_sel_hi:[0,1]
	s_waitcnt lgkmcnt(2)
	v_mfma_f32_16x16x32_bf16 v[34:37], v[34:37], v[54:57], v[38:41]
	v_mul_f32_e64 v46, v68, v46
	v_mul_f32_e64 v47, v68, v47
	v_pk_mul_f32 v[52:53], v[68:69], v[52:53] op_sel_hi:[0,1]
	v_pk_mul_f32 v[50:51], v[68:69], v[50:51] op_sel_hi:[0,1]
	ds_read_b128 v[38:41], v125 offset:24320
	s_waitcnt lgkmcnt(2)
	v_mfma_f32_16x16x32_bf16 v[30:33], v[30:33], v[54:57], v[58:61]
	s_nop 2
	ds_read_b128 v[58:61], v125 offset:31232
	s_waitcnt lgkmcnt(1)
	v_mfma_f32_16x16x32_bf16 v[38:41], v[38:41], v[54:57], v[62:65]
	s_waitcnt lgkmcnt(0)
	v_mfma_f32_16x16x32_bf16 v[62:65], v[58:61], v[54:57], v[132:135]
	ds_read_b128 v[58:61], v125 offset:33536
	v_mfma_f32_16x16x32_bf16 v[42:45], v[42:45], v[54:57], v[46:49]
	s_nop 2
	ds_read_b128 v[46:49], v125 offset:28928
	s_waitcnt lgkmcnt(0)
	v_mfma_f32_16x16x32_bf16 v[46:49], v[46:49], v[54:57], v[128:131]
	v_mfma_f32_16x16x32_bf16 v[54:57], v[58:61], v[54:57], v[50:53]
	s_nop 2
	ds_read_b128 v[50:53], v121 offset:54912
	ds_read_b128 v[128:131], v121 offset:54928
	ds_read_b128 v[58:61], v122 offset:35904
	s_waitcnt lgkmcnt(0)
	v_lshlrev_b32_e32 v68, 16, v58
	v_and_b32_e32 v58, 0xffff0000, v58
	v_mul_f32_e32 v50, v50, v68
	v_mul_f32_e32 v51, v51, v58
	v_cvt_pk_bf16_f32 v58, v50, v51
	v_lshlrev_b32_e32 v50, 16, v59
	v_and_b32_e32 v51, 0xffff0000, v59
	v_mul_f32_e32 v50, v52, v50
	v_mul_f32_e32 v51, v53, v51
	v_cvt_pk_bf16_f32 v59, v50, v51
	v_lshlrev_b32_e32 v50, 16, v60
	v_and_b32_e32 v51, 0xffff0000, v60
	v_mul_f32_e32 v50, v128, v50
	v_mul_f32_e32 v51, v129, v51
	v_cvt_pk_bf16_f32 v60, v50, v51
	v_lshlrev_b32_e32 v50, 16, v61
	v_and_b32_e32 v51, 0xffff0000, v61
	v_mul_f32_e32 v50, v130, v50
	v_mul_f32_e32 v51, v131, v51
	v_cvt_pk_bf16_f32 v61, v50, v51
	ds_read_b128 v[50:53], v125 offset:17472
	s_waitcnt lgkmcnt(0)
	v_mfma_f32_16x16x32_bf16 v[50:53], v[50:53], v[58:61], v[26:29]
	s_nop 2
	ds_read_b128 v[26:29], v125 offset:19776
	s_waitcnt lgkmcnt(0)
	v_mfma_f32_16x16x32_bf16 v[26:29], v[26:29], v[58:61], v[30:33]
	s_nop 2
	ds_read_b128 v[30:33], v125 offset:22080
	s_waitcnt lgkmcnt(0)
	v_mfma_f32_16x16x32_bf16 v[30:33], v[30:33], v[58:61], v[34:37]
	s_nop 2
	ds_read_b128 v[34:37], v125 offset:24384
	s_waitcnt lgkmcnt(0)
	v_mfma_f32_16x16x32_bf16 v[34:37], v[34:37], v[58:61], v[38:41]
	s_nop 2
	ds_read_b128 v[38:41], v125 offset:26688
	s_waitcnt lgkmcnt(0)
	v_mfma_f32_16x16x32_bf16 v[38:41], v[38:41], v[58:61], v[42:45]
	s_nop 2
	ds_read_b128 v[42:45], v125 offset:28992
	s_waitcnt lgkmcnt(0)
	v_mfma_f32_16x16x32_bf16 v[42:45], v[42:45], v[58:61], v[46:49]
	s_nop 2
	ds_read_b128 v[46:49], v125 offset:31296
	s_waitcnt lgkmcnt(0)
	v_mfma_f32_16x16x32_bf16 v[46:49], v[46:49], v[58:61], v[62:65]
	s_nop 2
	ds_read_b128 v[62:65], v125 offset:33600
	s_waitcnt lgkmcnt(0)
	s_barrier
	v_mfma_f32_16x16x32_bf16 v[54:57], v[62:65], v[58:61], v[54:57]
	s_cbranch_vccnz .LBB0_65
	s_add_i32 s18, s42, s49
	s_mov_b32 s35, 1
	s_add_i32 s34, s35, 1
	s_add_i32 s19, s35, 2
	s_cmp_ge_u32 s19, s48
	s_cbranch_scc1 .Lscan_O_pad
	s_add_i32 s49, s28, s35
	s_add_i32 s56, s49, 2
	s_ashr_i32 s57, s56, 31
	s_ashr_i32 s19, s18, 31
	s_lshl_b64 s[58:59], s[56:57], 16
	s_add_u32 s58, s27, s58
	s_addc_u32 s59, s29, s59
	s_lshl_b64 s[56:57], s[56:57], 18
	s_lshl_b32 s49, s47, 13
	s_or_b32 s56, s56, s49
	v_lshl_add_u64 v[220:221], v[86:87], 0, s[18:19]
	v_lshl_add_u64 v[236:237], v[78:79], 0, s[56:57]
	v_lshl_add_u64 v[228:229], v[88:89], 0, s[18:19]
	v_lshlrev_b64 v[220:221], 10, v[220:221]
	v_lshlrev_b64 v[228:229], 10, v[228:229]
	v_add_co_u32_e32 v240, vcc, 0x2000, v236
	v_lshl_add_u64 v[220:221], v[92:93], 0, v[220:221]
	v_lshl_add_u64 v[224:225], s[58:59], 0, v[76:77]
	v_lshl_add_u64 v[232:233], v[92:93], 0, v[228:229]
	v_lshl_add_u64 v[238:239], s[58:59], 0, v[90:91]
	v_addc_co_u32_e32 v241, vcc, 0, v237, vcc
	global_load_dwordx4 v[220:223], v[220:221], off
	s_nop 0
	global_load_dwordx4 v[224:227], v[224:225], off
	s_nop 0
	global_load_dwordx4 v[228:231], v[236:237], off
	s_nop 0
	global_load_dwordx4 v[232:235], v[232:233], off
	s_nop 0
	global_load_dwordx4 v[236:239], v[238:239], off
	s_nop 0
	global_load_dwordx4 v[240:243], v[240:241], off
	s_and_b64 vcc, exec, s[16:17]
	s_cbranch_vccnz .Lscan_O_pad
	v_mov_b32_e32 v59, s19
	v_or_b32_e32 v58, s18, v158
	v_lshlrev_b64 v[58:59], 7, v[58:59]
	v_lshl_add_u64 v[58:59], s[30:31], 0, v[58:59]
	global_load_dword v244, v[58:59], off
.Lscan_O_pad:
	global_load_dword v252, v[92:93], off
	global_load_dword v252, v[92:93], off
	global_load_dword v252, v[92:93], off
	global_load_dword v252, v[92:93], off
	global_load_dword v252, v[92:93], off
	global_load_dword v252, v[92:93], off
	global_load_dword v252, v[92:93], off
	global_load_dword v252, v[92:93], off
	s_cmp_ge_u32 s34, s48
	s_cbranch_scc1 .LBB0_108
.LBB0_106:
	s_bitcmp1_b32 s34, 0
	s_cbranch_scc1 .Lscan_B106
	s_bitcmp1_b32 s34, 0
	s_cselect_b32 s19, 0xd800, 0
	s_add_i32 s19, s19, 0
	v_lshl_add_u32 v58, v71, 1, s19
	v_lshl_add_u32 v59, v102, 1, s19
	v_add_u32_e32 v60, v58, v106
	s_waitcnt vmcnt(19)
	ds_write_b128 v60, v[2:5]
	v_add_u32_e32 v60, v59, v107
	v_add_u32_e32 v58, v58, v108
	s_waitcnt vmcnt(18)
	ds_write_b128 v60, v[6:9] offset:17408
	s_waitcnt vmcnt(17)
	ds_write_b128 v60, v[10:13] offset:35840
	s_waitcnt vmcnt(16)
	ds_write_b128 v58, v[14:17]
	v_add_u32_e32 v58, v59, v109
	s_and_b64 vcc, exec, s[16:17]
	s_waitcnt vmcnt(15)
	ds_write_b128 v58, v[18:21] offset:17408
	s_waitcnt vmcnt(14)
	ds_write_b128 v60, v[22:25] offset:45056
	s_cbranch_vccnz .LBB0_108
	v_cmp_lt_i32_e32 vcc, v194, v193
	v_mul_f32_e64 v58, v126, -v0
	s_add_i32 s19, s19, s50
	v_cndmask_b32_e32 v59, v194, v192, vcc
	v_lshlrev_b32_e32 v59, 2, v59
	ds_bpermute_b32 v59, v59, v58
	v_cmp_lt_i32_e32 vcc, v195, v193
	s_waitcnt lgkmcnt(0)
	v_fma_f32 v59, v126, -v0, v59
	v_cndmask_b32_e32 v60, v195, v192, vcc
	v_cndmask_b32_e64 v58, v59, v58, s[4:5]
	v_lshlrev_b32_e32 v59, 2, v60
	ds_bpermute_b32 v59, v59, v58
	v_cmp_lt_i32_e32 vcc, v196, v193
	s_waitcnt lgkmcnt(0)
	v_add_f32_e32 v59, v58, v59
	v_cndmask_b32_e32 v60, v196, v192, vcc
	v_lshlrev_b32_e32 v60, 2, v60
	v_cndmask_b32_e64 v58, v59, v58, s[6:7]
	ds_bpermute_b32 v59, v60, v58
	v_cmp_lt_i32_e32 vcc, v197, v193
	s_waitcnt lgkmcnt(0)
	v_add_f32_e32 v59, v58, v59
	v_cndmask_b32_e32 v60, v197, v192, vcc
	v_lshlrev_b32_e32 v60, 2, v60
	v_cndmask_b32_e64 v58, v59, v58, s[8:9]
	ds_bpermute_b32 v59, v60, v58
	v_cmp_lt_i32_e32 vcc, v198, v193
	s_waitcnt lgkmcnt(0)
	v_add_f32_e32 v59, v58, v59
	v_cndmask_b32_e32 v60, v198, v192, vcc
	v_lshlrev_b32_e32 v60, 2, v60
	v_cndmask_b32_e64 v58, v59, v58, s[10:11]
	ds_bpermute_b32 v59, v60, v58
	v_cmp_lt_i32_e32 vcc, v199, v193
	s_waitcnt lgkmcnt(0)
	v_add_f32_e32 v59, v58, v59
	v_cndmask_b32_e32 v60, v199, v192, vcc
	v_lshlrev_b32_e32 v60, 2, v60
	v_cndmask_b32_e64 v58, v59, v58, s[12:13]
	ds_bpermute_b32 v59, v60, v58
	v_lshl_add_u32 v60, v158, 2, s19
	s_waitcnt lgkmcnt(0)
	v_add_f32_e32 v59, v58, v59
	v_cndmask_b32_e64 v58, v59, v58, s[14:15]
	v_lshl_or_b32 v59, v192, 2, v200
	ds_bpermute_b32 v59, v59, v58
	s_waitcnt lgkmcnt(0)
	v_sub_f32_e32 v59, v59, v58
	v_mul_f32_e32 v59, 0x3fb8aa3b, v59
	v_exp_f32_e32 v59, v59
	s_nop 0
	v_mul_f32_e32 v59, v126, v59
	ds_write2st64_b32 v60, v58, v59 offset0:212 offset1:214
.LBB0_108:
	s_add_i32 s19, s35, 3
	s_cmp_ge_u32 s19, s48
	s_cbranch_scc1 .Lscan_skip
	s_add_i32 s49, s28, s35
	s_add_i32 s56, s49, 3
	s_ashr_i32 s57, s56, 31
	s_add_i32 s74, s18, 64
	s_ashr_i32 s75, s74, 31
	s_lshl_b64 s[58:59], s[56:57], 16
	s_add_u32 s58, s27, s58
	s_addc_u32 s59, s29, s59
	s_lshl_b64 s[56:57], s[56:57], 18
	s_lshl_b32 s49, s47, 13
	s_or_b32 s56, s56, s49
	v_lshl_add_u64 v[2:3], v[86:87], 0, s[74:75]
	v_lshl_add_u64 v[18:19], v[78:79], 0, s[56:57]
	v_lshl_add_u64 v[10:11], v[88:89], 0, s[74:75]
	v_lshlrev_b64 v[2:3], 10, v[2:3]
	v_lshlrev_b64 v[10:11], 10, v[10:11]
	v_add_co_u32_e32 v22, vcc, 0x2000, v18
	v_lshl_add_u64 v[2:3], v[92:93], 0, v[2:3]
	v_lshl_add_u64 v[6:7], s[58:59], 0, v[76:77]
	v_lshl_add_u64 v[14:15], v[92:93], 0, v[10:11]
	v_lshl_add_u64 v[20:21], s[58:59], 0, v[90:91]
	v_addc_co_u32_e32 v23, vcc, 0, v19, vcc
	global_load_dwordx4 v[2:5], v[2:3], off
	s_nop 0
	global_load_dwordx4 v[6:9], v[6:7], off
	s_nop 0
	global_load_dwordx4 v[10:13], v[18:19], off
	s_nop 0
	global_load_dwordx4 v[14:17], v[14:15], off
	s_nop 0
	global_load_dwordx4 v[18:21], v[20:21], off
	s_nop 0
	global_load_dwordx4 v[22:25], v[22:23], off
	s_and_b64 vcc, exec, s[16:17]
	s_cbranch_vccnz .LBB0_111
	v_mov_b32_e32 v59, s75
	v_or_b32_e32 v58, s74, v158
	v_lshlrev_b64 v[58:59], 7, v[58:59]
	v_lshl_add_u64 v[58:59], s[30:31], 0, v[58:59]
	global_load_dword v126, v[58:59], off
	s_branch .LBB0_111
.Lscan_skip:
	global_load_dword v252, v[92:93], off
	global_load_dword v252, v[92:93], off
	global_load_dword v252, v[92:93], off
	global_load_dword v252, v[92:93], off
	global_load_dword v252, v[92:93], off
	global_load_dword v252, v[92:93], off
	global_load_dword v252, v[92:93], off
	s_branch .LBB0_111
.Lscan_B106:
	s_bitcmp1_b32 s34, 0
	s_cselect_b32 s19, 0xd800, 0
	s_add_i32 s19, s19, 0
	v_lshl_add_u32 v58, v71, 1, s19
	v_lshl_add_u32 v59, v102, 1, s19
	v_add_u32_e32 v60, v58, v106
	s_waitcnt vmcnt(19)
	ds_write_b128 v60, v[220:223]
	v_add_u32_e32 v60, v59, v107
	v_add_u32_e32 v58, v58, v108
	s_waitcnt vmcnt(18)
	ds_write_b128 v60, v[224:227] offset:17408
	s_waitcnt vmcnt(17)
	ds_write_b128 v60, v[228:231] offset:35840
	s_waitcnt vmcnt(16)
	ds_write_b128 v58, v[232:235]
	v_add_u32_e32 v58, v59, v109
	s_and_b64 vcc, exec, s[16:17]
	s_waitcnt vmcnt(15)
	ds_write_b128 v58, v[236:239] offset:17408
	s_waitcnt vmcnt(14)
	ds_write_b128 v60, v[240:243] offset:45056
	s_cbranch_vccnz .Lscan_B108
	v_cmp_lt_i32_e32 vcc, v194, v193
	v_mul_f32_e64 v58, v244, -v0
	s_add_i32 s19, s19, s50
	v_cndmask_b32_e32 v59, v194, v192, vcc
	v_lshlrev_b32_e32 v59, 2, v59
	ds_bpermute_b32 v59, v59, v58
	v_cmp_lt_i32_e32 vcc, v195, v193
	s_waitcnt lgkmcnt(0)
	v_fma_f32 v59, v244, -v0, v59
	v_cndmask_b32_e32 v60, v195, v192, vcc
	v_cndmask_b32_e64 v58, v59, v58, s[4:5]
	v_lshlrev_b32_e32 v59, 2, v60
	ds_bpermute_b32 v59, v59, v58
	v_cmp_lt_i32_e32 vcc, v196, v193
	s_waitcnt lgkmcnt(0)
	v_add_f32_e32 v59, v58, v59
	v_cndmask_b32_e32 v60, v196, v192, vcc
	v_lshlrev_b32_e32 v60, 2, v60
	v_cndmask_b32_e64 v58, v59, v58, s[6:7]
	ds_bpermute_b32 v59, v60, v58
	v_cmp_lt_i32_e32 vcc, v197, v193
	s_waitcnt lgkmcnt(0)
	v_add_f32_e32 v59, v58, v59
	v_cndmask_b32_e32 v60, v197, v192, vcc
	v_lshlrev_b32_e32 v60, 2, v60
	v_cndmask_b32_e64 v58, v59, v58, s[8:9]
	ds_bpermute_b32 v59, v60, v58
	v_cmp_lt_i32_e32 vcc, v198, v193
	s_waitcnt lgkmcnt(0)
	v_add_f32_e32 v59, v58, v59
	v_cndmask_b32_e32 v60, v198, v192, vcc
	v_lshlrev_b32_e32 v60, 2, v60
	v_cndmask_b32_e64 v58, v59, v58, s[10:11]
	ds_bpermute_b32 v59, v60, v58
	v_cmp_lt_i32_e32 vcc, v199, v193
	s_waitcnt lgkmcnt(0)
	v_add_f32_e32 v59, v58, v59
	v_cndmask_b32_e32 v60, v199, v192, vcc
	v_lshlrev_b32_e32 v60, 2, v60
	v_cndmask_b32_e64 v58, v59, v58, s[12:13]
	ds_bpermute_b32 v59, v60, v58
	v_lshl_add_u32 v60, v158, 2, s19
	s_waitcnt lgkmcnt(0)
	v_add_f32_e32 v59, v58, v59
	v_cndmask_b32_e64 v58, v59, v58, s[14:15]
	v_lshl_or_b32 v59, v192, 2, v200
	ds_bpermute_b32 v59, v59, v58
	s_waitcnt lgkmcnt(0)
	v_sub_f32_e32 v59, v59, v58
	v_mul_f32_e32 v59, 0x3fb8aa3b, v59
	v_exp_f32_e32 v59, v59
	s_nop 0
	v_mul_f32_e32 v59, v244, v59
	ds_write2st64_b32 v60, v58, v59 offset0:212 offset1:214
.Lscan_B108:
	s_add_i32 s19, s35, 3
	s_cmp_ge_u32 s19, s48
	s_cbranch_scc1 .Lscan_skip
	s_add_i32 s49, s28, s35
	s_add_i32 s56, s49, 3
	s_ashr_i32 s57, s56, 31
	s_add_i32 s74, s18, 64
	s_ashr_i32 s75, s74, 31
	s_lshl_b64 s[58:59], s[56:57], 16
	s_add_u32 s58, s27, s58
	s_addc_u32 s59, s29, s59
	s_lshl_b64 s[56:57], s[56:57], 18
	s_lshl_b32 s49, s47, 13
	s_or_b32 s56, s56, s49
	v_lshl_add_u64 v[220:221], v[86:87], 0, s[74:75]
	v_lshl_add_u64 v[236:237], v[78:79], 0, s[56:57]
	v_lshl_add_u64 v[228:229], v[88:89], 0, s[74:75]
	v_lshlrev_b64 v[220:221], 10, v[220:221]
	v_lshlrev_b64 v[228:229], 10, v[228:229]
	v_add_co_u32_e32 v240, vcc, 0x2000, v236
	v_lshl_add_u64 v[220:221], v[92:93], 0, v[220:221]
	v_lshl_add_u64 v[224:225], s[58:59], 0, v[76:77]
	v_lshl_add_u64 v[232:233], v[92:93], 0, v[228:229]
	v_lshl_add_u64 v[238:239], s[58:59], 0, v[90:91]
	v_addc_co_u32_e32 v241, vcc, 0, v237, vcc
	global_load_dwordx4 v[220:223], v[220:221], off
	s_nop 0
	global_load_dwordx4 v[224:227], v[224:225], off
	s_nop 0
	global_load_dwordx4 v[228:231], v[236:237], off
	s_nop 0
	global_load_dwordx4 v[232:235], v[232:233], off
	s_nop 0
	global_load_dwordx4 v[236:239], v[238:239], off
	s_nop 0
	global_load_dwordx4 v[240:243], v[240:241], off
	s_and_b64 vcc, exec, s[16:17]
	s_cbranch_vccnz .LBB0_111
	v_mov_b32_e32 v59, s75
	v_or_b32_e32 v58, s74, v158
	v_lshlrev_b64 v[58:59], 7, v[58:59]
	v_lshl_add_u64 v[58:59], s[30:31], 0, v[58:59]
	global_load_dword v244, v[58:59], off

.LBB0_158:
	s_mov_b64 s[74:75], 0x1800
	s_min_i32 s32, s46, s42
	s_mul_hi_i32 s47, s32, 0x2aaaaaab
	s_lshr_b32 s50, s47, 31
	s_ashr_i32 s47, s47, 3
	s_add_i32 s47, s47, s50
	s_mul_i32 s50, s47, 0xffffffd0
	s_add_i32 s50, s50, s32
	s_lshl_b32 s47, s47, 6
	s_lshl_b32 s50, s50, 6
	v_or_b32_e32 v228, s50, v56
	v_mov_b32_e32 v229, 0
	v_lshl_add_u64 v[228:229], v[228:229], 1, s[6:7]
	v_add_u32_e32 v232, s47, v57
	v_mad_i64_i32 v[230:231], s[98:99], v232, s67, v[228:229]
	global_load_dwordx4 v[142:145], v[230:231], off
	v_lshl_add_u64 v[230:231], v[230:231], 0, s[74:75]
	global_load_dwordx4 v[146:149], v[230:231], off
	v_lshl_add_u64 v[230:231], v[230:231], 0, s[74:75]
	global_load_dwordx4 v[150:153], v[230:231], off
	v_lshl_add_u64 v[230:231], v[230:231], 0, s[74:75]
	global_load_dwordx4 v[162:165], v[230:231], off
	s_add_i32 s32, s46, s76
	s_min_i32 s32, s32, s42
	s_mul_hi_i32 s47, s32, 0x2aaaaaab
	s_lshr_b32 s50, s47, 31
	s_ashr_i32 s47, s47, 3
	s_add_i32 s47, s47, s50
	s_mul_i32 s50, s47, 0xffffffd0
	s_add_i32 s50, s50, s32
	s_lshl_b32 s47, s47, 6
	s_lshl_b32 s50, s50, 6
	v_or_b32_e32 v228, s50, v56
	v_mov_b32_e32 v229, 0
	v_lshl_add_u64 v[228:229], v[228:229], 1, s[6:7]
	v_add_u32_e32 v232, s47, v57
	v_mad_i64_i32 v[230:231], s[98:99], v232, s67, v[228:229]
	global_load_dwordx4 v[166:169], v[230:231], off
	v_lshl_add_u64 v[230:231], v[230:231], 0, s[74:75]
	global_load_dwordx4 v[170:173], v[230:231], off
	v_lshl_add_u64 v[230:231], v[230:231], 0, s[74:75]
	global_load_dwordx4 v[174:177], v[230:231], off
	v_lshl_add_u64 v[230:231], v[230:231], 0, s[74:75]
	global_load_dwordx4 v[178:181], v[230:231], off
	s_add_i32 s32, s46, s43
	s_min_i32 s32, s32, s42
	s_mul_hi_i32 s47, s32, 0x2aaaaaab
	s_lshr_b32 s50, s47, 31
	s_ashr_i32 s47, s47, 3
	s_add_i32 s47, s47, s50
	s_mul_i32 s50, s47, 0xffffffd0
	s_add_i32 s50, s50, s32
	s_lshl_b32 s47, s47, 6
	s_lshl_b32 s50, s50, 6
	v_or_b32_e32 v228, s50, v56
	v_mov_b32_e32 v229, 0
	v_lshl_add_u64 v[228:229], v[228:229], 1, s[6:7]
	v_add_u32_e32 v232, s47, v57
	v_mad_i64_i32 v[230:231], s[98:99], v232, s67, v[228:229]
	global_load_dwordx4 v[182:185], v[230:231], off
	v_lshl_add_u64 v[230:231], v[230:231], 0, s[74:75]
	global_load_dwordx4 v[186:189], v[230:231], off
	v_lshl_add_u64 v[230:231], v[230:231], 0, s[74:75]
	global_load_dwordx4 v[220:223], v[230:231], off
	v_lshl_add_u64 v[230:231], v[230:231], 0, s[74:75]
	global_load_dwordx4 v[224:227], v[230:231], off
	s_min_i32 s4, s46, s42
	s_mul_hi_i32 s5, s4, 0x2aaaaaab
	s_lshr_b32 s18, s5, 31
	s_ashr_i32 s5, s5, 3
	s_add_i32 s18, s5, s18
	s_mul_i32 s5, s18, 0xffffffd0
	s_lshl_b32 s19, s18, 6
	s_add_i32 s20, s5, s4
	s_add_i32 s4, s19, s92
	s_add_i32 s5, s4, 0xffff8000
	s_lshr_b32 s5, s5, 6
	s_lshl_b32 s22, s20, 6
	s_add_i32 s5, s5, 16
	s_ashr_i32 s21, s4, 11
	s_cmp_lt_i32 s4, 0x8000
	s_cselect_b32 s4, 0x7c0, 0
	s_cselect_b32 s21, s21, s5
	s_and_b32 s4, s4, s19
	s_cmp_gt_i32 s21, 15
	v_or_b32_e32 v52, s22, v56
	v_add_u32_e32 v2, s4, v54
	s_cselect_b64 s[4:5], -1, 0
	s_add_i32 s21, s21, -16
	v_ashrrev_i32_e32 v53, 31, v52
	v_cndmask_b32_e64 v0, 0, 1, s[4:5]
	s_mul_hi_u32 s25, s21, 3
	s_mul_i32 s24, s21, 3
	s_waitcnt lgkmcnt(0)
	v_lshl_add_u64 v[4:5], v[52:53], 2, s[16:17]
	v_cmp_gt_i32_e32 vcc, 3, v2
	v_cmp_ne_u32_e64 s[4:5], 1, v0
	s_and_saveexec_b64 s[26:27], vcc
	s_xor_b64 s[26:27], exec, s[26:27]
	s_cbranch_execz .LBB0_161
	s_waitcnt vmcnt(0)
	v_mov_b32_e32 v13, 0
	s_and_b64 vcc, exec, s[4:5]
	v_mov_b32_e32 v99, 0
	v_mov_b32_e32 v11, 0
	v_mov_b32_e32 v103, 0
	v_mov_b32_e32 v100, 0
	v_mov_b32_e32 v40, 0
	v_mov_b32_e32 v106, 0
	v_mov_b32_e32 v38, 0
	s_cbranch_vccnz .LBB0_161
	v_ashrrev_i32_e32 v3, 31, v2
	v_lshl_add_u64 v[6:7], s[24:25], 0, v[2:3]
	v_mad_u64_u32 v[8:9], s[28:29], v6, s86, v[4:5]
	v_mad_i32_i24 v9, v7, s86, v9
	global_load_dwordx4 v[10:13], v[8:9], off offset:16
	global_load_dwordx4 v[38:41], v[8:9], off
	s_waitcnt vmcnt(1)
	v_mov_b32_e32 v99, v12
	v_mov_b32_e32 v103, v10
	s_waitcnt vmcnt(0)
	v_mov_b32_e32 v100, v41
	v_mov_b32_e32 v106, v39
.LBB0_161:
	s_or_saveexec_b64 s[26:27], s[26:27]
	v_add_u32_e32 v0, s19, v57
	s_waitcnt vmcnt(11)
	v_lshl_add_u64 v[6:7], v[52:53], 1, s[6:7]
	s_xor_b64 exec, exec, s[26:27]
	s_cbranch_execz .LBB0_163
	v_mad_i64_i32 v[8:9], s[28:29], v0, s67, v[6:7]
	s_waitcnt vmcnt(11)
	s_nop 0
	v_lshlrev_b32_e32 v38, 16, v142
	v_and_b32_e32 v106, 0xffff0000, v142
	v_lshlrev_b32_e32 v40, 16, v143
	v_and_b32_e32 v100, 0xffff0000, v143
	v_lshlrev_b32_e32 v103, 16, v144
	v_and_b32_e32 v11, 0xffff0000, v144
	v_lshlrev_b32_e32 v99, 16, v145
	v_and_b32_e32 v13, 0xffff0000, v145

.LBB0_166:
	s_andn2_saveexec_b64 s[26:27], s[26:27]
	s_cbranch_execz .LBB0_168
	v_add_u32_e32 v3, 1, v0
	v_mad_i64_i32 v[8:9], s[28:29], v3, s67, v[6:7]
	s_waitcnt vmcnt(10)
	s_nop 0
	v_lshlrev_b32_e32 v39, 16, v146
	v_and_b32_e32 v107, 0xffff0000, v146
	v_lshlrev_b32_e32 v41, 16, v147
	v_and_b32_e32 v101, 0xffff0000, v147
	v_lshlrev_b32_e32 v102, 16, v148
	v_and_b32_e32 v10, 0xffff0000, v148
	v_lshlrev_b32_e32 v98, 16, v149
	v_and_b32_e32 v12, 0xffff0000, v149

.LBB0_171:
.LBB0_172:
	s_andn2_saveexec_b64 s[26:27], s[26:27]
	s_cbranch_execz .LBB0_174
	v_add_u32_e32 v0, 2, v0
	v_mad_i64_i32 v[8:9], s[28:29], v0, s67, v[6:7]
	s_waitcnt vmcnt(9)
	s_nop 0
	v_lshlrev_b32_e32 v46, 16, v150
	v_and_b32_e32 v112, 0xffff0000, v150
	v_lshlrev_b32_e32 v48, 16, v151
	v_and_b32_e32 v108, 0xffff0000, v151
	v_lshlrev_b32_e32 v111, 16, v152
	v_and_b32_e32 v43, 0xffff0000, v152
	v_lshlrev_b32_e32 v105, 16, v153
	v_and_b32_e32 v45, 0xffff0000, v153

.LBB0_177:
.LBB0_178:
	s_andn2_saveexec_b64 s[4:5], s[26:27]
	s_cbranch_execz .LBB0_180
	v_add_u32_e32 v0, s19, v54
	v_mad_i64_i32 v[2:3], s[24:25], v0, s67, v[6:7]
	s_waitcnt vmcnt(8)
	s_nop 0
	v_lshlrev_b32_e32 v47, 16, v162
	v_and_b32_e32 v113, 0xffff0000, v162
	v_lshlrev_b32_e32 v49, 16, v163
	v_and_b32_e32 v109, 0xffff0000, v163
	v_lshlrev_b32_e32 v110, 16, v164
	v_and_b32_e32 v42, 0xffff0000, v164
	v_lshlrev_b32_e32 v104, 16, v165
	v_and_b32_e32 v44, 0xffff0000, v165

.LBB0_183:
	s_or_saveexec_b64 s[34:35], s[34:35]
	v_add_u32_e32 v0, s25, v57
	v_lshl_add_u64 v[6:7], v[50:51], 1, s[6:7]
	s_xor_b64 exec, exec, s[34:35]
	s_cbranch_execz .LBB0_185
	v_mad_i64_i32 v[8:9], s[36:37], v0, s67, v[6:7]
	s_waitcnt vmcnt(7)
	s_nop 0
	v_lshlrev_b32_e32 v34, 16, v166
	v_and_b32_e32 v96, 0xffff0000, v166
	v_lshlrev_b32_e32 v36, 16, v167
	v_and_b32_e32 v92, 0xffff0000, v167
	v_lshlrev_b32_e32 v95, 16, v168
	v_and_b32_e32 v31, 0xffff0000, v168
	v_lshlrev_b32_e32 v91, 16, v169
	v_and_b32_e32 v33, 0xffff0000, v169

.LBB0_188:
	s_andn2_saveexec_b64 s[34:35], s[34:35]
	s_cbranch_execz .LBB0_190
	v_add_u32_e32 v3, 1, v0
	v_mad_i64_i32 v[8:9], s[36:37], v3, s67, v[6:7]
	s_waitcnt vmcnt(6)
	s_nop 0
	v_lshlrev_b32_e32 v35, 16, v170
	v_and_b32_e32 v97, 0xffff0000, v170
	v_lshlrev_b32_e32 v37, 16, v171
	v_and_b32_e32 v93, 0xffff0000, v171
	v_lshlrev_b32_e32 v94, 16, v172
	v_and_b32_e32 v30, 0xffff0000, v172
	v_lshlrev_b32_e32 v90, 16, v173
	v_and_b32_e32 v32, 0xffff0000, v173

.LBB0_193:
.LBB0_194:
	s_andn2_saveexec_b64 s[34:35], s[34:35]
	s_cbranch_execz .LBB0_196
	v_add_u32_e32 v0, 2, v0
	v_mad_i64_i32 v[8:9], s[36:37], v0, s67, v[6:7]
	s_waitcnt vmcnt(5)
	s_nop 0
	v_lshlrev_b32_e32 v26, 16, v174
	v_and_b32_e32 v86, 0xffff0000, v174
	v_lshlrev_b32_e32 v28, 16, v175
	v_and_b32_e32 v84, 0xffff0000, v175
	v_lshlrev_b32_e32 v89, 16, v176
	v_and_b32_e32 v23, 0xffff0000, v176
	v_lshlrev_b32_e32 v83, 16, v177
	v_and_b32_e32 v25, 0xffff0000, v177

.LBB0_199:
.LBB0_200:
	s_andn2_saveexec_b64 s[4:5], s[34:35]
	s_cbranch_execz .LBB0_202
	v_add_u32_e32 v0, s25, v54
	v_mad_i64_i32 v[2:3], s[30:31], v0, s67, v[6:7]
	s_waitcnt vmcnt(4)
	s_nop 0
	v_lshlrev_b32_e32 v27, 16, v178
	v_and_b32_e32 v87, 0xffff0000, v178
	v_lshlrev_b32_e32 v29, 16, v179
	v_and_b32_e32 v85, 0xffff0000, v179
	v_lshlrev_b32_e32 v88, 16, v180
	v_and_b32_e32 v22, 0xffff0000, v180
	v_lshlrev_b32_e32 v82, 16, v181
	v_and_b32_e32 v24, 0xffff0000, v181

.LBB0_205:
	s_or_saveexec_b64 s[40:41], s[40:41]
	v_add_u32_e32 v0, s31, v57
	v_lshl_add_u64 v[118:119], v[76:77], 1, s[6:7]
	s_xor_b64 exec, exec, s[40:41]
	s_cbranch_execz .LBB0_207
	v_mad_i64_i32 v[2:3], s[48:49], v0, s67, v[118:119]
	s_waitcnt vmcnt(3)
	s_nop 0
	v_lshlrev_b32_e32 v18, 16, v182
	v_and_b32_e32 v80, 0xffff0000, v182
	v_lshlrev_b32_e32 v20, 16, v183
	v_and_b32_e32 v74, 0xffff0000, v183
	v_lshlrev_b32_e32 v79, 16, v184
	v_and_b32_e32 v15, 0xffff0000, v184
	v_lshlrev_b32_e32 v73, 16, v185
	v_and_b32_e32 v17, 0xffff0000, v185

.LBB0_210:
	s_andn2_saveexec_b64 s[40:41], s[40:41]
	s_cbranch_execz .LBB0_212
	v_add_u32_e32 v2, 1, v0
	v_mad_i64_i32 v[2:3], s[48:49], v2, s67, v[118:119]
	s_waitcnt vmcnt(2)
	s_nop 0
	v_lshlrev_b32_e32 v19, 16, v186
	v_and_b32_e32 v81, 0xffff0000, v186
	v_lshlrev_b32_e32 v21, 16, v187
	v_and_b32_e32 v75, 0xffff0000, v187
	v_lshlrev_b32_e32 v78, 16, v188
	v_and_b32_e32 v14, 0xffff0000, v188
	v_lshlrev_b32_e32 v72, 16, v189
	v_and_b32_e32 v16, 0xffff0000, v189

.LBB0_215:
.LBB0_216:
	s_andn2_saveexec_b64 s[40:41], s[40:41]
	s_cbranch_execz .LBB0_218
	v_add_u32_e32 v0, 2, v0
	v_mad_i64_i32 v[2:3], s[48:49], v0, s67, v[118:119]
	s_waitcnt vmcnt(1)
	s_nop 0
	v_lshlrev_b32_e32 v6, 16, v220
	v_and_b32_e32 v68, 0xffff0000, v220
	v_lshlrev_b32_e32 v8, 16, v221
	v_and_b32_e32 v64, 0xffff0000, v221
	v_lshlrev_b32_e32 v71, 16, v222
	v_and_b32_e32 v3, 0xffff0000, v222
	v_lshlrev_b32_e32 v67, 16, v223
	v_and_b32_e32 v5, 0xffff0000, v223

.LBB0_221:
.LBB0_222:
	s_andn2_saveexec_b64 s[4:5], s[40:41]
	s_cbranch_execz .LBB0_224
	v_add_u32_e32 v0, s31, v54
	v_mad_i64_i32 v[114:115], s[38:39], v0, s67, v[118:119]
	s_waitcnt vmcnt(0)
	s_nop 0
	v_lshlrev_b32_e32 v7, 16, v224
	v_and_b32_e32 v69, 0xffff0000, v224
	v_lshlrev_b32_e32 v9, 16, v225
	v_and_b32_e32 v65, 0xffff0000, v225
	v_lshlrev_b32_e32 v70, 16, v226
	v_and_b32_e32 v2, 0xffff0000, v226
	v_lshlrev_b32_e32 v66, 16, v227
	v_and_b32_e32 v4, 0xffff0000, v227
